# attention tile loop: softmax VALU sections at s_setprio 1, MFMA groups at priority 0
# baseline (speedup 1.0000x reference)
; #define LAS __attribute__((address_space(3)))
; DEV void attn_tile(LAS unsigned char* lds, const bf16x8 (&qf)[2][2], int tl, int kpos0, int mode, bool near, bool rowsel, const float (&cbias)[2],
;                    unsigned kb, unsigned vb_, unsigned btb, int g4, float (&mrun)[2], float (&lrun)[2], f32x4 (&O)[2][4]) {
;     f32x4 sc[2][4];
;     float ci[2];
; #pragma unroll
;     for (int hh = 0; hh < 2; ++hh) { const float mne = mrun[hh] < -1e29f ? 0.f : mrun[hh];
;         ci[hh] = near ? -mne : (((mode == 1 && !rowsel) ? NEG_ : cbias[hh]) - mne); }
;     {
;         bf16x8 kf[4][2];
; #pragma unroll
;         for (int kt = 0; kt < 4; ++kt) { kf[kt][0] = *(const LAS bf16x8*)(lds + kb + kt * 2304); kf[kt][1] = *(const LAS bf16x8*)(lds + kb + kt * 2304 + 64); }
;         __builtin_amdgcn_sched_barrier(0);
; #pragma unroll
;         for (int kt = 0; kt < 4; ++kt)
; #pragma unroll
;             for (int hh = 0; hh < 2; ++hh) sc[hh][kt] = __builtin_amdgcn_mfma_f32_16x16x32_bf16(kf[kt][0], qf[hh][0], (f32x4){ci[hh], ci[hh], ci[hh], ci[hh]}, 0, 0, 0);
; #pragma unroll
;         for (int kt = 0; kt < 4; ++kt)
; #pragma unroll
;             for (int hh = 0; hh < 2; ++hh) sc[hh][kt] = __builtin_amdgcn_mfma_f32_16x16x32_bf16(kf[kt][1], qf[hh][1], sc[hh][kt], 0, 0, 0);
;     }
.Lst_xx:
	s_mov_b32 s101, s99
	s_cmp_ge_i32 s50, s36
	s_cselect_b64 s[4:5], -1, 0
	s_cmp_eq_u32 s97, 2
	s_cselect_b64 s[6:7], -1, 0
	s_cmp_eq_u32 s50, s17
	s_cselect_b64 s[42:43], -1, 0
	s_and_b64 s[6:7], s[6:7], s[42:43]
	s_or_b64 s[4:5], s[4:5], s[6:7]
	v_lshrrev_b32_e32 v64, s50, v127
	v_and_b32_e32 v64, 1, v64
	s_cmp_lg_u32 s97, 1
	v_cmp_eq_u32_e64 s[48:49], 1, v64
	s_cselect_b64 s[6:7], -1, 0
	s_or_b64 vcc, s[6:7], s[48:49]
	v_cmp_gt_f32_e64 s[44:45], s65, v149
	v_cndmask_b32_e32 v65, v223, v136, vcc
	v_cmp_gt_f32_e64 s[42:43], s65, v150
	v_cndmask_b32_e64 v64, v149, 0, s[44:45]
	v_sub_f32_e32 v65, v65, v64
	v_cndmask_b32_e64 v64, v65, -v64, s[4:5]
	v_cndmask_b32_e64 v65, v150, 0, s[42:43]
	v_cndmask_b32_e32 v66, v223, v137, vcc
	v_sub_f32_e32 v66, v66, v65
	v_cndmask_b32_e64 v68, v66, -v65, s[4:5]
	v_mov_b32_e32 v65, v64
	v_mov_b32_e32 v66, v64
	v_mov_b32_e32 v67, v64
	v_mov_b32_e32 v69, v68
	v_mov_b32_e32 v70, v68
	v_mov_b32_e32 v71, v68
	s_waitcnt lgkmcnt(7)
	s_setprio 0
	v_mfma_f32_16x16x32_bf16 v[162:165], v[72:75], v[8:11], v[64:67]
	s_mov_b64 s[6:7], -1
	s_and_b64 vcc, exec, s[4:5]
	v_mfma_f32_16x16x32_bf16 v[72:75], v[72:75], v[16:19], v[68:71]
	v_add_u32_e32 v228, s98, v145
	v_add_u32_e32 v229, 0x800, v228
	v_add_u32_e32 v230, 0x1000, v228
	v_add_u32_e32 v231, 0x1800, v228
	ds_read2_b64 v[232:235], v228 offset1:4
	ds_read2_b64 v[236:239], v228 offset0:8 offset1:12
	ds_read2_b64 v[240:243], v229 offset0:32 offset1:36
	ds_read2_b64 v[244:247], v229 offset0:40 offset1:44
	ds_read2_b64 v[248:251], v230 offset0:64 offset1:68
	ds_read2_b64 v[198:201], v230 offset0:72 offset1:76
	ds_read2_b64 v[202:205], v231 offset0:96 offset1:100
	ds_read2_b64 v[206:209], v231 offset0:104 offset1:108
	s_waitcnt lgkmcnt(13)
	v_mfma_f32_16x16x32_bf16 v[166:169], v[80:83], v[8:11], v[64:67]
	v_mfma_f32_16x16x32_bf16 v[80:83], v[80:83], v[16:19], v[68:71]
	s_waitcnt lgkmcnt(11)
	v_mfma_f32_16x16x32_bf16 v[180:183], v[88:91], v[8:11], v[64:67]
	v_mfma_f32_16x16x32_bf16 v[184:187], v[88:91], v[16:19], v[68:71]
	s_waitcnt lgkmcnt(9)
	v_mfma_f32_16x16x32_bf16 v[188:191], v[92:95], v[8:11], v[64:67]
	v_mfma_f32_16x16x32_bf16 v[68:71], v[92:95], v[16:19], v[68:71]
	v_mfma_f32_16x16x32_bf16 v[92:95], v[76:79], v[12:15], v[162:165]
	v_mfma_f32_16x16x32_bf16 v[76:79], v[76:79], v[20:23], v[72:75]
	v_mfma_f32_16x16x32_bf16 v[88:91], v[84:87], v[12:15], v[166:169]
	v_mfma_f32_16x16x32_bf16 v[72:75], v[84:87], v[20:23], v[80:83]
	v_mfma_f32_16x16x32_bf16 v[84:87], v[154:157], v[12:15], v[180:183]
	v_mfma_f32_16x16x32_bf16 v[64:67], v[154:157], v[20:23], v[184:187]
	s_waitcnt lgkmcnt(8)
	v_mfma_f32_16x16x32_bf16 v[80:83], v[158:161], v[12:15], v[188:191]
	v_mfma_f32_16x16x32_bf16 v[68:71], v[158:161], v[20:23], v[68:71]
	s_setprio 1
	s_cbranch_vccnz .LBB0_271
	s_mov_b64 s[6:7], 0

; #define LAS __attribute__((address_space(3)))
; #define OPQV(x) asm volatile("" : "+v"(x))
; DEV void kv_store(LAS unsigned char* lds, const KVRegs& r, int buf, int tid) {
;     const int key = tid >> 3, c8 = (tid & 7) * 8;
;     unsigned kw = AT_KS + buf * 9216 + (key * 72 + c8) * 2, vw = AT_VT + buf * 9216 + ((tid >> 6) * 8 * 72 + (tid & 63)) * 2; OPQV(kw); OPQV(vw);
;     *(LAS u32x4*)(lds + kw) = r.k;
; #pragma unroll
;     for (int j = 0; j < 4; ++j) { *(LAS bf16_t*)(lds + vw + j * 288) = (bf16_t)(r.v[j] & 0xffffu); *(LAS bf16_t*)(lds + vw + j * 288 + 144) = (bf16_t)(r.v[j] >> 16); }
; }
; DEV void attn_item(LAS unsigned char* lds, const bf16_t* P, const bf16_t* QB, const bf16_t* KV, const bf16_t* KC, const bf16_t* VC, const float* rel_bias, bf16_t* OB, int b, int g, int qt) {
;     ...
;             kv_store(lds, pre, buf, tid);
;             __syncthreads();
.Lst_zz:
	s_setprio 0
	s_min_u32 s100, s100, 1
	s_andn2_b64 vcc, exec, s[92:93]
	s_cbranch_vccz .Lst_exit
	s_xor_b32 s98, s98, 0x2400
	v_add_u32_e32 v228, s98, v139
	v_add_u32_e32 v229, s98, v146
	s_waitcnt vmcnt(1)
	ds_write_b128 v228, v[24:27]
	s_waitcnt vmcnt(0)
	ds_write_b16 v229, v28
	ds_write_b16_d16_hi v229, v28 offset:144
	ds_write_b16 v229, v29 offset:288
	ds_write_b16_d16_hi v229, v29 offset:432
	ds_write_b16 v229, v30 offset:576
	ds_write_b16_d16_hi v229, v30 offset:720
	ds_write_b16 v229, v31 offset:864
	ds_write_b16_d16_hi v229, v31 offset:1008
	s_waitcnt lgkmcnt(0)
	s_barrier
	s_mov_b32 s97, s96
	s_mov_b32 s50, s52
	s_branch .LBB0_260

; #define LAS __attribute__((address_space(3)))
; DEV unsigned cvt_pk_bf16(float lo, float hi) { unsigned r; asm volatile("v_cvt_pk_bf16_f32 %0, %1, %2" : "=v"(r) : "v"(lo), "v"(hi)); return r; }
; DEV void attn_tile(LAS unsigned char* lds, const bf16x8 (&qf)[2][2], int tl, int kpos0, int mode, bool near, bool rowsel, const float (&cbias)[2],
;                    unsigned kb, unsigned vb_, unsigned btb, int g4, float (&mrun)[2], float (&lrun)[2], f32x4 (&O)[2][4]) {
;     ...
;         float rs = 0.f;
; #pragma unroll
;         for (int kt = 0; kt < 4; ++kt)
; #pragma unroll
;             for (int r = 0; r < 4; ++r) { const float p = __builtin_amdgcn_exp2f(sc[hh][kt][r]); sc[hh][kt][r] = p; rs += p; }
;         lrun[hh] += rs;
; #pragma unroll
;         for (int kc = 0; kc < 2; ++kc) { u32x4 w; w.x = cvt_pk_bf16(sc[hh][2 * kc][0], sc[hh][2 * kc][1]); w.y = cvt_pk_bf16(sc[hh][2 * kc][2], sc[hh][2 * kc][3]);
;             w.z = cvt_pk_bf16(sc[hh][2 * kc + 1][0], sc[hh][2 * kc + 1][1]); w.w = cvt_pk_bf16(sc[hh][2 * kc + 1][2], sc[hh][2 * kc + 1][3]); pf[hh][kc] = as_bf16x8(w); }
;     }
; #pragma unroll
;     for (int dt = 0; dt < 4; ++dt)
; #pragma unroll
;         for (int kc = 0; kc < 2; ++kc) {
;             const u32x2 va = *(const LAS u32x2*)(lds + vb_ + dt * 2304 + kc * 64);
;             const u32x2 vb = *(const LAS u32x2*)(lds + vb_ + dt * 2304 + kc * 64 + 32);
;             const bf16x8 vf = as_bf16x8((u32x4){va.x, va.y, vb.x, vb.y});
; #pragma unroll
;             for (int hh = 0; hh < 2; ++hh) O[hh][dt] = __builtin_amdgcn_mfma_f32_16x16x32_bf16(vf, pf[hh][kc], O[hh][dt], 0, 0, 0);
;         }
; }
.Lst_y_entry:
	s_setprio 1
	v_exp_f32_e32 v92, v92
	v_exp_f32_e32 v93, v93
	v_exp_f32_e32 v94, v94
	v_exp_f32_e32 v95, v95
	v_exp_f32_e32 v88, v88
	v_exp_f32_e32 v89, v89
	v_exp_f32_e32 v90, v90
	v_exp_f32_e32 v91, v91
	v_exp_f32_e32 v153, v84
	v_exp_f32_e32 v154, v85
	v_exp_f32_e32 v155, v86
	v_exp_f32_e32 v156, v87
	v_exp_f32_e32 v157, v80
	v_exp_f32_e32 v158, v81
	v_exp_f32_e32 v159, v82
	v_exp_f32_e32 v160, v83
	v_cvt_pk_bf16_f32 v162, v92, v93
	v_cvt_pk_bf16_f32 v163, v94, v95
	v_cvt_pk_bf16_f32 v164, v88, v89
	v_cvt_pk_bf16_f32 v165, v90, v91
	v_cvt_pk_bf16_f32 v166, v153, v154
	v_cvt_pk_bf16_f32 v167, v155, v156
	v_cvt_pk_bf16_f32 v168, v157, v158
	v_cvt_pk_bf16_f32 v169, v159, v160
	v_add_f32_e32 v92, 0, v92
	v_add_f32_e32 v92, v93, v92
	v_add_f32_e32 v92, v94, v92
	v_add_f32_e32 v92, v95, v92
	v_add_f32_e32 v88, v88, v92
	v_add_f32_e32 v88, v89, v88
	v_add_f32_e32 v88, v90, v88
	v_add_f32_e32 v88, v91, v88
	v_add_f32_e32 v88, v153, v88
	v_add_f32_e32 v88, v154, v88
	v_add_f32_e32 v88, v155, v88
	v_add_f32_e32 v88, v156, v88
	v_add_f32_e32 v88, v157, v88
	v_exp_f32_e32 v76, v76
	v_add_f32_e32 v88, v158, v88
	v_exp_f32_e32 v77, v77
	v_add_f32_e32 v88, v159, v88
	v_exp_f32_e32 v78, v78
	v_add_f32_e32 v88, v160, v88
	v_exp_f32_e32 v79, v79
	v_add_f32_e32 v151, v151, v88
	v_add_f32_e32 v88, 0, v76
	v_exp_f32_e32 v72, v72
	v_add_f32_e32 v88, v77, v88
	v_exp_f32_e32 v73, v73
	v_add_f32_e32 v88, v78, v88
	v_exp_f32_e32 v74, v74
	v_add_f32_e32 v88, v79, v88
	v_exp_f32_e32 v75, v75
	v_add_f32_e32 v88, v72, v88
	v_exp_f32_e32 v64, v64
	v_add_f32_e32 v88, v73, v88
	v_exp_f32_e32 v65, v65
	v_add_f32_e32 v88, v74, v88
	v_exp_f32_e32 v66, v66
	v_add_f32_e32 v88, v75, v88
	v_exp_f32_e32 v67, v67
	v_add_f32_e32 v88, v64, v88
	v_exp_f32_e32 v89, v68
	v_add_f32_e32 v88, v65, v88
	v_add_f32_e32 v88, v66, v88
	v_add_f32_e32 v88, v67, v88
	v_add_f32_e32 v68, v89, v88
	v_exp_f32_e32 v88, v69
	v_exp_f32_e32 v90, v70
	v_exp_f32_e32 v91, v71
	v_add_f32_e32 v68, v88, v68
	v_add_f32_e32 v68, v90, v68
	v_add_f32_e32 v68, v91, v68
	v_add_f32_e32 v148, v148, v68
	v_cvt_pk_bf16_f32 v68, v76, v77
	v_cvt_pk_bf16_f32 v69, v78, v79
	v_cvt_pk_bf16_f32 v70, v72, v73
	v_cvt_pk_bf16_f32 v71, v74, v75
	v_cvt_pk_bf16_f32 v64, v64, v65
	v_cvt_pk_bf16_f32 v65, v66, v67
	v_cvt_pk_bf16_f32 v66, v89, v88
	v_cvt_pk_bf16_f32 v67, v90, v91
	s_cmp_eq_u32 s100, 1
	s_cbranch_scc0 .Lst_nokpre
	v_add_u32_e32 v228, s98, v141
	ds_read_b128 v[72:75], v228
	ds_read_b128 v[76:79], v228 offset:64
	ds_read_b128 v[80:83], v228 offset:2304
	ds_read_b128 v[84:87], v228 offset:2368
	ds_read_b128 v[88:91], v228 offset:4608
	ds_read_b128 v[154:157], v228 offset:4672
	ds_read_b128 v[92:95], v228 offset:6912
	ds_read_b128 v[158:161], v228 offset:6976
.Lst_nokpre:
	s_waitcnt lgkmcnt(7)
	s_setprio 0
	v_mfma_f32_16x16x32_bf16 v[44:47], v[232:235], v[162:165], v[44:47]
	v_mfma_f32_16x16x32_bf16 v[32:35], v[232:235], v[68:71], v[32:35]
	s_waitcnt lgkmcnt(6)
	v_mfma_f32_16x16x32_bf16 v[44:47], v[236:239], v[166:169], v[44:47]
	v_mfma_f32_16x16x32_bf16 v[32:35], v[236:239], v[64:67], v[32:35]
	s_waitcnt lgkmcnt(5)
	v_mfma_f32_16x16x32_bf16 v[56:59], v[240:243], v[162:165], v[56:59]
	v_mfma_f32_16x16x32_bf16 v[40:43], v[240:243], v[68:71], v[40:43]
	s_waitcnt lgkmcnt(4)
	v_mfma_f32_16x16x32_bf16 v[56:59], v[244:247], v[166:169], v[56:59]
	v_mfma_f32_16x16x32_bf16 v[40:43], v[244:247], v[64:67], v[40:43]
	s_waitcnt lgkmcnt(3)
	v_mfma_f32_16x16x32_bf16 v[52:55], v[248:251], v[162:165], v[52:55]
	v_mfma_f32_16x16x32_bf16 v[36:39], v[248:251], v[68:71], v[36:39]
	s_waitcnt lgkmcnt(2)
	v_mfma_f32_16x16x32_bf16 v[52:55], v[198:201], v[166:169], v[52:55]
	v_mfma_f32_16x16x32_bf16 v[36:39], v[198:201], v[64:67], v[36:39]
	s_waitcnt lgkmcnt(1)
	v_mfma_f32_16x16x32_bf16 v[48:51], v[202:205], v[68:71], v[48:51]
	v_mfma_f32_16x16x32_bf16 v[60:63], v[202:205], v[162:165], v[60:63]
	s_waitcnt lgkmcnt(0)
	v_mfma_f32_16x16x32_bf16 v[60:63], v[206:209], v[166:169], v[60:63]
	v_mfma_f32_16x16x32_bf16 v[48:51], v[206:209], v[64:67], v[48:51]
	s_bitcmp1_b32 s101, 8
	s_cbranch_scc0 .LBB0_283
	ds_bpermute_b32 v64, v143, v151
	s_and_b32 s6, s101, 0xff
	s_lshl_b32 s6, s6, 1
	v_mov_b32_e32 v66, 0
	s_waitcnt lgkmcnt(0)
	v_add_f32_e32 v64, v151, v64
	ds_bpermute_b32 v65, v144, v64
	s_waitcnt lgkmcnt(0)
	v_add_f32_e32 v65, v64, v65
	v_mov_b32_e32 v64, 0
	v_cmp_lt_f32_e32 vcc, 0, v65
	s_and_saveexec_b64 s[4:5], vcc
	s_cbranch_execz .LBB0_280
	s_cmp_eq_u32 s6, 1
	s_cselect_b64 vcc, -1, 0
	s_cmp_eq_u32 s6, 2
	v_cndmask_b32_e32 v66, v126, v7, vcc
	s_cselect_b64 vcc, -1, 0
	s_cmp_eq_u32 s6, 3
	v_cndmask_b32_e32 v66, v66, v2, vcc
	s_cselect_b64 vcc, -1, 0
	s_cmp_eq_u32 s6, 4
	v_cndmask_b32_e32 v66, v66, v3, vcc
	s_cselect_b64 vcc, -1, 0
	s_cmp_eq_u32 s6, 5
	v_cndmask_b32_e32 v66, v66, v4, vcc
	s_cselect_b64 vcc, -1, 0
	v_cndmask_b32_e32 v66, v66, v5, vcc
	v_div_scale_f32 v67, s[42:43], v65, v65, v66
	v_rcp_f32_e32 v68, v67
	s_nop 0
	v_fma_f32 v69, -v67, v68, 1.0
	v_fmac_f32_e32 v68, v69, v68
	v_div_scale_f32 v69, vcc, v66, v65, v66
	v_mul_f32_e32 v70, v69, v68
	v_fma_f32 v71, -v67, v70, v69
	v_fmac_f32_e32 v70, v71, v68
	v_fma_f32 v67, -v67, v70, v69
	v_div_fmas_f32 v67, v67, v68, v70
	v_div_fixup_f32 v66, v67, v65, v66
